# grid barrier: non-leader workgroups poll the cross-XCD release generation directly (one polling hop less), on top of scan in-register transpose + prologue batching
# speedup vs baseline: 1.0090x; 1.0052x over previous
.LBB0_103:
	s_or_b64 exec, exec, s[10:11]
	v_cvt_f32_u32_e32 v4, v2
	s_waitcnt vmcnt(0)
	v_readfirstlane_b32 s8, v3
	v_sub_u32_e32 v3, 0, v2
	v_rcp_iflag_f32_e32 v4, v4
	v_add_u32_e32 v5, s8, v1
	v_mul_f32_e32 v4, 0x4f7ffffe, v4
	v_cvt_u32_f32_e32 v4, v4
	v_mul_lo_u32 v1, v3, v4
	v_mul_hi_u32 v1, v4, v1
	v_add_u32_e32 v1, v4, v1
	v_mul_hi_u32 v1, v5, v1
	v_mul_lo_u32 v3, v1, v2
	v_sub_u32_e32 v3, v5, v3
	v_add_u32_e32 v4, 1, v1
	v_cmp_ge_u32_e32 vcc, v3, v2
	s_nop 1
	v_cndmask_b32_e32 v1, v1, v4, vcc
	v_sub_u32_e32 v4, v3, v2
	v_cndmask_b32_e32 v3, v3, v4, vcc
	v_add_u32_e32 v4, 1, v1
	v_cmp_ge_u32_e32 vcc, v3, v2
	v_add_u32_e32 v3, 1, v5
	s_nop 0
	v_cndmask_b32_e32 v1, v1, v4, vcc
	v_mul_lo_u32 v4, v2, v1
	v_add_u32_e32 v2, v4, v2
	v_cmp_ne_u32_e32 vcc, v3, v2
	s_and_saveexec_b64 s[8:9], vcc
	s_xor_b64 s[8:9], exec, s[8:9]
	s_cbranch_execz .LBB0_117
	s_waitcnt lgkmcnt(0)
	v_mov_b32_e32 v0, 0x3100
	global_load_dword v0, v0, s[40:41] offset:1024 sc1
	s_add_u32 s14, s40, 0x3500
	s_addc_u32 s15, s41, 0
	s_waitcnt vmcnt(0)
	v_cmp_eq_u32_e32 vcc, v0, v1
	s_and_saveexec_b64 s[10:11], vcc
	s_cbranch_execz .LBB0_116
	s_add_u32 s12, s38, 0x1b000200
	s_addc_u32 s13, s39, 0
	s_mov_b32 s26, 1
	s_mov_b64 s[16:17], 0
	v_mov_b32_e32 v0, 0
	s_branch .LBB0_107

.LBB0_219:
	s_or_b64 exec, exec, s[14:15]
	v_cvt_f32_u32_e32 v4, v2
	s_waitcnt vmcnt(0)
	v_readfirstlane_b32 s6, v3
	v_sub_u32_e32 v3, 0, v2
	v_rcp_iflag_f32_e32 v4, v4
	v_add_u32_e32 v5, s6, v1
	v_mul_f32_e32 v4, 0x4f7ffffe, v4
	v_cvt_u32_f32_e32 v4, v4
	v_mul_lo_u32 v1, v3, v4
	v_mul_hi_u32 v1, v4, v1
	v_add_u32_e32 v1, v4, v1
	v_mul_hi_u32 v1, v5, v1
	v_mul_lo_u32 v3, v1, v2
	v_sub_u32_e32 v3, v5, v3
	v_add_u32_e32 v4, 1, v1
	v_cmp_ge_u32_e32 vcc, v3, v2
	s_nop 1
	v_cndmask_b32_e32 v1, v1, v4, vcc
	v_sub_u32_e32 v4, v3, v2
	v_cndmask_b32_e32 v3, v3, v4, vcc
	v_add_u32_e32 v4, 1, v1
	v_cmp_ge_u32_e32 vcc, v3, v2
	v_add_u32_e32 v3, 1, v5
	s_nop 0
	v_cndmask_b32_e32 v1, v1, v4, vcc
	v_mul_lo_u32 v4, v2, v1
	v_add_u32_e32 v2, v4, v2
	v_cmp_ne_u32_e32 vcc, v3, v2
	s_and_saveexec_b64 s[6:7], vcc
	s_xor_b64 s[12:13], exec, s[6:7]
	s_cbranch_execz .LBB0_233
	s_waitcnt lgkmcnt(0)
	v_mov_b32_e32 v0, 0x3100
	global_load_dword v0, v0, s[40:41] offset:1024 sc1
	s_add_u32 s18, s40, 0x3500
	s_addc_u32 s19, s41, 0
	s_waitcnt vmcnt(0)
	v_cmp_eq_u32_e32 vcc, v0, v1
	s_and_saveexec_b64 s[14:15], vcc
	s_cbranch_execz .LBB0_232
	s_add_u32 s16, s38, 0x1b000200
	s_addc_u32 s17, s39, 0
	s_mov_b32 s6, 1
	s_mov_b64 s[20:21], 0
	v_mov_b32_e32 v0, 0
	s_branch .LBB0_223

.LBB0_284:
	s_or_b64 exec, exec, s[14:15]
	v_cvt_f32_u32_e32 v4, v2
	s_waitcnt vmcnt(0)
	v_readfirstlane_b32 s12, v3
	v_sub_u32_e32 v3, 0, v2
	v_rcp_iflag_f32_e32 v4, v4
	v_add_u32_e32 v5, s12, v1
	v_mul_f32_e32 v4, 0x4f7ffffe, v4
	v_cvt_u32_f32_e32 v4, v4
	v_mul_lo_u32 v1, v3, v4
	v_mul_hi_u32 v1, v4, v1
	v_add_u32_e32 v1, v4, v1
	v_mul_hi_u32 v1, v5, v1
	v_mul_lo_u32 v3, v1, v2
	v_sub_u32_e32 v3, v5, v3
	v_add_u32_e32 v4, 1, v1
	v_cmp_ge_u32_e32 vcc, v3, v2
	s_nop 1
	v_cndmask_b32_e32 v1, v1, v4, vcc
	v_sub_u32_e32 v4, v3, v2
	v_cndmask_b32_e32 v3, v3, v4, vcc
	v_add_u32_e32 v4, 1, v1
	v_cmp_ge_u32_e32 vcc, v3, v2
	v_add_u32_e32 v3, 1, v5
	s_nop 0
	v_cndmask_b32_e32 v1, v1, v4, vcc
	v_mul_lo_u32 v4, v2, v1
	v_add_u32_e32 v2, v4, v2
	v_cmp_ne_u32_e32 vcc, v3, v2
	s_and_saveexec_b64 s[12:13], vcc
	s_xor_b64 s[12:13], exec, s[12:13]
	s_cbranch_execz .LBB0_298
	s_waitcnt lgkmcnt(0)
	v_mov_b32_e32 v0, 0x3100
	global_load_dword v0, v0, s[40:41] offset:1024 sc1
	s_add_u32 s18, s40, 0x3500
	s_addc_u32 s19, s41, 0
	s_waitcnt vmcnt(0)
	v_cmp_eq_u32_e32 vcc, v0, v1
	s_and_saveexec_b64 s[14:15], vcc
	s_cbranch_execz .LBB0_297
	s_add_u32 s16, s38, 0x1b000200
	s_addc_u32 s17, s39, 0
	s_mov_b32 s34, 1
	s_mov_b64 s[20:21], 0
	v_mov_b32_e32 v0, 0
	s_branch .LBB0_288

.LBB0_993:
	s_or_b64 exec, exec, s[12:13]
	v_cvt_f32_u32_e32 v4, v2
	s_waitcnt vmcnt(0)
	v_readfirstlane_b32 s10, v3
	v_sub_u32_e32 v3, 0, v2
	v_rcp_iflag_f32_e32 v4, v4
	v_add_u32_e32 v5, s10, v1
	v_mul_f32_e32 v4, 0x4f7ffffe, v4
	v_cvt_u32_f32_e32 v4, v4
	v_mul_lo_u32 v1, v3, v4
	v_mul_hi_u32 v1, v4, v1
	v_add_u32_e32 v1, v4, v1
	v_mul_hi_u32 v1, v5, v1
	v_mul_lo_u32 v3, v1, v2
	v_sub_u32_e32 v3, v5, v3
	v_add_u32_e32 v4, 1, v1
	v_cmp_ge_u32_e32 vcc, v3, v2
	s_nop 1
	v_cndmask_b32_e32 v1, v1, v4, vcc
	v_sub_u32_e32 v4, v3, v2
	v_cndmask_b32_e32 v3, v3, v4, vcc
	v_add_u32_e32 v4, 1, v1
	v_cmp_ge_u32_e32 vcc, v3, v2
	v_add_u32_e32 v3, 1, v5
	s_nop 0
	v_cndmask_b32_e32 v1, v1, v4, vcc
	v_mul_lo_u32 v4, v2, v1
	v_add_u32_e32 v2, v4, v2
	v_cmp_ne_u32_e32 vcc, v3, v2
	s_and_saveexec_b64 s[10:11], vcc
	s_xor_b64 s[10:11], exec, s[10:11]
	s_cbranch_execz .LBB0_1007
	s_waitcnt lgkmcnt(0)
	v_mov_b32_e32 v0, 0x3100
	global_load_dword v0, v0, s[40:41] offset:1024 sc1
	s_add_u32 s16, s40, 0x3500
	s_addc_u32 s17, s41, 0
	s_waitcnt vmcnt(0)
	v_cmp_eq_u32_e32 vcc, v0, v1
	s_and_saveexec_b64 s[12:13], vcc
	s_cbranch_execz .LBB0_1006
	s_add_u32 s14, s38, 0x1b000200
	s_addc_u32 s15, s39, 0
	s_mov_b32 s30, 1
	s_mov_b64 s[18:19], 0
	v_mov_b32_e32 v0, 0
	s_branch .LBB0_997

.LBB0_1268:
	s_or_b64 exec, exec, s[10:11]
	v_cvt_f32_u32_e32 v20, v18
	s_waitcnt vmcnt(0)
	v_readfirstlane_b32 s4, v19
	v_sub_u32_e32 v19, 0, v18
	v_rcp_iflag_f32_e32 v20, v20
	v_add_u32_e32 v21, s4, v17
	v_mul_f32_e32 v20, 0x4f7ffffe, v20
	v_cvt_u32_f32_e32 v20, v20
	v_mul_lo_u32 v17, v19, v20
	v_mul_hi_u32 v17, v20, v17
	v_add_u32_e32 v17, v20, v17
	v_mul_hi_u32 v17, v21, v17
	v_mul_lo_u32 v19, v17, v18
	v_sub_u32_e32 v19, v21, v19
	v_add_u32_e32 v20, 1, v17
	v_cmp_ge_u32_e32 vcc, v19, v18
	s_nop 1
	v_cndmask_b32_e32 v17, v17, v20, vcc
	v_sub_u32_e32 v20, v19, v18
	v_cndmask_b32_e32 v19, v19, v20, vcc
	v_add_u32_e32 v20, 1, v17
	v_cmp_ge_u32_e32 vcc, v19, v18
	v_add_u32_e32 v19, 1, v21
	s_nop 0
	v_cndmask_b32_e32 v17, v17, v20, vcc
	v_mul_lo_u32 v20, v18, v17
	v_add_u32_e32 v18, v20, v18
	v_cmp_ne_u32_e32 vcc, v19, v18
	s_and_saveexec_b64 s[4:5], vcc
	s_xor_b64 s[4:5], exec, s[4:5]
	s_cbranch_execz .LBB0_1282
	s_waitcnt lgkmcnt(0)
	v_mov_b32_e32 v16, 0x3100
	global_load_dword v16, v16, s[40:41] offset:1024 sc1
	s_add_u32 s14, s40, 0x3500
	s_addc_u32 s15, s41, 0
	s_waitcnt vmcnt(0)
	v_cmp_eq_u32_e32 vcc, v16, v17
	s_and_saveexec_b64 s[10:11], vcc
	s_cbranch_execz .LBB0_1281
	s_add_u32 s12, s38, 0x1b000200
	s_addc_u32 s13, s39, 0
	s_mov_b32 s26, 1
	s_mov_b64 s[16:17], 0
	v_mov_b32_e32 v16, 0
	s_branch .LBB0_1272
